# prep_x and final_norm: next row touched early (scratch loads issued behind the current row's loads) so the next iteration hits the cache
# speedup vs baseline: 1.0206x; 1.0206x over previous
.LBB0_226:
	v_lshl_add_u64 v[14:15], s[12:13], 0, v[4:5]
	v_add_co_u32_e64 v26, s[4:5], s0, v14
	s_waitcnt lgkmcnt(0)
	s_nop 1
	v_addc_co_u32_e64 v27, s[4:5], 0, v15, s[4:5]
	global_load_dwordx4 v[10:13], v[6:7], off offset:-2048
	global_load_dwordx4 v[14:17], v[6:7], off offset:-1024
	global_load_dwordx4 v[18:21], v[6:7], off
	global_load_dwordx4 v[22:25], v[6:7], off offset:1024
	s_add_i32 s101, s8, s10
	s_cmpk_lt_i32 s101, 0x4000
	s_cselect_b32 s98, s18, 0
	s_cselect_b32 s99, s19, 0
	v_lshl_add_u64 v[236:237], v[6:7], 0, s[98:99]
	global_load_dwordx4 v[238:241], v[236:237], off offset:-2048
	global_load_dwordx4 v[238:241], v[236:237], off offset:-1024
	global_load_dwordx4 v[238:241], v[236:237], off
	global_load_dwordx4 v[238:241], v[236:237], off offset:1024
	s_waitcnt vmcnt(7)
	v_cvt_pk_bf16_f32 v230, v10, v11
	v_cvt_pk_bf16_f32 v231, v12, v13
	global_store_dwordx2 v[26:27], v[230:231], off
	s_waitcnt vmcnt(7)
	v_cvt_pk_bf16_f32 v232, v14, v15
	v_cvt_pk_bf16_f32 v233, v16, v17
	global_store_dwordx2 v[26:27], v[232:233], off offset:512
	s_waitcnt vmcnt(7)
	v_cvt_pk_bf16_f32 v234, v18, v19
	v_cvt_pk_bf16_f32 v235, v20, v21
	global_store_dwordx2 v[26:27], v[234:235], off offset:1024
	v_mul_f32_e32 v11, v11, v11
	v_mul_f32_e32 v13, v13, v13
	v_fmac_f32_e32 v11, v10, v10
	v_fmac_f32_e32 v13, v12, v12
	v_add_f32_e32 v10, v11, v13
	v_mul_f32_e32 v11, v15, v15
	v_mul_f32_e32 v12, v17, v17
	v_fmac_f32_e32 v11, v14, v14
	v_fmac_f32_e32 v12, v16, v16
	v_add_f32_e32 v11, v11, v12
	v_add_f32_e32 v10, v10, v11
	v_mul_f32_e32 v11, v19, v19
	v_mul_f32_e32 v12, v21, v21
	v_fmac_f32_e32 v11, v18, v18
	v_fmac_f32_e32 v12, v20, v20
	v_add_f32_e32 v11, v11, v12
	v_add_f32_e32 v10, v10, v11
	s_waitcnt vmcnt(7)
	v_mul_f32_e32 v11, v23, v23
	v_mul_f32_e32 v12, v25, v25
	v_fmac_f32_e32 v11, v22, v22
	v_fmac_f32_e32 v12, v24, v24
	v_add_f32_e32 v11, v11, v12
	v_add_f32_e32 v10, v10, v11
	ds_bpermute_b32 v11, v8, v10
	v_cvt_pk_bf16_f32 v12, v22, v23
	v_cvt_pk_bf16_f32 v13, v24, v25
	global_store_dwordx2 v[26:27], v[12:13], off offset:1536
	s_waitcnt lgkmcnt(0)
	v_add_f32_e32 v10, v10, v11
	ds_bpermute_b32 v11, v9, v10
	s_and_saveexec_b64 s[4:5], vcc
	s_cbranch_execz .LBB0_225
	s_waitcnt lgkmcnt(0)
	v_add_f32_e32 v12, v10, v11
	v_lshl_add_u64 v[10:11], s[12:13], 0, v[2:3]
	global_store_dword v[10:11], v12, off
	s_branch .LBB0_225

.LBB0_3405:
	global_load_dwordx4 v[6:9], v1, s[2:3]
	global_load_dwordx4 v[10:13], v1, s[2:3] offset:16
	global_load_dwordx4 v[14:17], v1, s[2:3] offset:32
	global_load_dwordx4 v[18:21], v1, s[2:3] offset:48
	global_load_dwordx4 v[22:25], v[4:5], off offset:-2048
	global_load_dwordx4 v[30:33], v[4:5], off offset:-1024
	global_load_dwordx4 v[40:43], v[4:5], off
	global_load_dwordx4 v[44:47], v[4:5], off offset:1024
	s_add_i32 s11, s11, s0
	s_add_u32 s2, s2, s6
	s_addc_u32 s3, s3, s7
	s_cmpk_lt_i32 s11, 0x4000
	s_cselect_b32 s98, s8, 0
	s_cselect_b32 s99, s9, 0
	v_lshl_add_u64 v[236:237], v[4:5], 0, s[98:99]
	global_load_dwordx4 v[238:241], v1, s[2:3]
	global_load_dwordx4 v[238:241], v[236:237], off offset:-2048
	global_load_dwordx4 v[238:241], v[236:237], off offset:-1024
	global_load_dwordx4 v[238:241], v[236:237], off
	global_load_dwordx4 v[238:241], v[236:237], off offset:1024
	s_waitcnt vmcnt(12)
	v_mov_b32_e32 v34, v7
	v_mov_b32_e32 v35, v8
	v_mov_b32_e32 v7, v9
	s_waitcnt vmcnt(11)
	v_mov_b32_e32 v8, v11
	v_mov_b32_e32 v9, v12
	v_mov_b32_e32 v11, v13
	v_pk_add_f32 v[6:7], v[34:35], v[6:7]
	v_pk_add_f32 v[8:9], v[8:9], v[10:11]
	v_pk_add_f32 v[6:7], v[6:7], v[6:7] op_sel:[0,1] op_sel_hi:[1,0]
	v_pk_add_f32 v[8:9], v[8:9], v[8:9] op_sel:[0,1] op_sel_hi:[1,0]
	s_waitcnt vmcnt(10)
	v_add_f32_e32 v12, v14, v15
	v_add_f32_e32 v14, v16, v17
	s_waitcnt vmcnt(9)
	v_mov_b32_e32 v13, v20
	v_mov_b32_e32 v15, v21
	v_mov_b32_e32 v7, v18
	v_mov_b32_e32 v9, v19
	v_pk_add_f32 v[10:11], v[12:13], v[14:15]
	v_pk_add_f32 v[6:7], v[6:7], v[8:9]
	s_nop 0
	v_pk_add_f32 v[6:7], v[6:7], v[10:11]
	s_nop 0
	v_add_f32_e32 v6, v6, v7
	v_fmamk_f32 v6, v6, 0x3a800000, v0
	v_mul_f32_e32 v7, 0x4b800000, v6
	v_cmp_gt_f32_e32 vcc, s1, v6
	s_nop 1
	v_cndmask_b32_e32 v6, v6, v7, vcc
	v_rsq_f32_e32 v6, v6
	s_nop 0
	v_mul_f32_e32 v7, 0x45800000, v6
	v_cndmask_b32_e32 v18, v6, v7, vcc
	s_waitcnt vmcnt(8)
	v_pk_mul_f32 v[64:65], v[22:23], v[18:19] op_sel_hi:[1,0]
	v_pk_mul_f32 v[66:67], v[24:25], v[18:19] op_sel_hi:[1,0]
	v_pk_mul_f32 v[64:65], v[48:49], v[64:65]
	v_pk_mul_f32 v[66:67], v[50:51], v[66:67]
	global_store_dwordx4 v[4:5], v[64:67], off offset:-2048
	s_waitcnt vmcnt(8)
	v_pk_mul_f32 v[68:69], v[30:31], v[18:19] op_sel_hi:[1,0]
	v_pk_mul_f32 v[70:71], v[32:33], v[18:19] op_sel_hi:[1,0]
	v_pk_mul_f32 v[68:69], v[52:53], v[68:69]
	v_pk_mul_f32 v[70:71], v[54:55], v[70:71]
	global_store_dwordx4 v[4:5], v[68:71], off offset:-1024
	s_waitcnt vmcnt(8)
	v_pk_mul_f32 v[72:73], v[40:41], v[18:19] op_sel_hi:[1,0]
	v_pk_mul_f32 v[74:75], v[42:43], v[18:19] op_sel_hi:[1,0]
	v_pk_mul_f32 v[72:73], v[56:57], v[72:73]
	v_pk_mul_f32 v[74:75], v[58:59], v[74:75]
	global_store_dwordx4 v[4:5], v[72:75], off
	s_waitcnt vmcnt(8)
	v_pk_mul_f32 v[76:77], v[44:45], v[18:19] op_sel_hi:[1,0]
	v_pk_mul_f32 v[78:79], v[46:47], v[18:19] op_sel_hi:[1,0]
	v_pk_mul_f32 v[76:77], v[60:61], v[76:77]
	v_pk_mul_f32 v[78:79], v[62:63], v[78:79]
	global_store_dwordx4 v[4:5], v[76:79], off offset:1024
	v_lshl_add_u64 v[4:5], v[4:5], 0, s[8:9]
	s_cbranch_scc1 .LBB0_3405
